# v16 + wide (8-byte) ppass stores via transposed MFMA output for retention and GLA + loop-invariant norm-gain loads hoisted out of rw_phase row loops
# speedup vs baseline: 1.0058x; 1.0058x over previous
; #define KP(f) ((decltype(Params::f))(char*)(gchar_t*)(char*)karg((int)offsetof(Params, f)))
; DI int otid() { int t = threadIdx.x; asm volatile("" : "+v"(t)); return t; }
; DI void rw_phase(const float* x, bf16_t* hb, const bf16_t* y, const float* gpost, float* rh, float* fout, bool y_unscaled) {
;   const int tid_ = otid(), wid = tid_ >> 6, lane = tid_ & 63;
;   for (int row = blockIdx.x * 8 + wid; row < T_; row += gridDim.x * 8) {
; __global__ void __launch_bounds__(512, 2) mega(Params p) {
;     ...
;       else if (ms == 2) {
;         rw_phase(nullptr, bU, bC, gl + 3072, rh, (lyr < 3) ? nullptr : KP(out), true);
;         if (lyr < 3) wconv_layer(lyr + 1, (float*)lds);
.LBB0_105:
	v_mov_b32_e32 v0, v159
	v_readlane_b32 s22, v254, 4
	v_ashrrev_i32_e32 v1, 6, v0
	s_nop 0
	v_add_u32_e32 v24, s22, v1
	v_cmp_gt_i32_e32 vcc, s53, v24
	s_and_saveexec_b64 s[22:23], vcc
	s_cbranch_execz .LBB0_465
	v_and_b32_e32 v2, 63, v0
	v_readlane_b32 s26, v255, 35
	v_lshlrev_b32_e32 v148, 4, v2
	v_readlane_b32 s27, v255, 36
	v_lshl_add_u64 v[26:27], s[30:31], 0, v[148:149]
	v_cmp_lt_i32_e32 vcc, v209, v208
	v_lshl_add_u64 v[28:29], s[26:27], 0, v[148:149]
	v_readlane_b32 s26, v255, 37
	v_lshlrev_b32_e32 v148, 5, v2
	v_readlane_b32 s27, v255, 38
	s_cmp_lg_u64 s[42:43], 0
	s_cselect_b64 s[38:39], -1, 0
	v_lshl_add_u64 v[0:1], s[26:27], 0, v[148:149]
	s_mov_b64 s[26:27], 0x3000
	v_lshl_add_u64 v[30:31], v[0:1], 0, s[26:27]
	v_cndmask_b32_e32 v0, v206, v209, vcc
	v_cmp_lt_i32_e32 vcc, v210, v208
	v_lshlrev_b32_e32 v62, 2, v0
	s_mov_b64 s[26:27], 0
	v_cndmask_b32_e32 v0, v206, v210, vcc
	v_cmp_lt_i32_e32 vcc, v211, v208
	v_lshlrev_b32_e32 v63, 2, v0
	v_lshl_add_u64 v[32:33], s[42:43], 0, v[148:149]
	v_cndmask_b32_e32 v0, v206, v211, vcc
	v_lshlrev_b32_e32 v64, 2, v0
	v_xor_b32_e32 v0, 8, v206
	v_cmp_lt_i32_e32 vcc, v0, v208
	v_cmp_eq_u32_e64 s[42:43], 0, v2
	s_nop 0
	v_cndmask_b32_e32 v0, v206, v0, vcc
	v_lshlrev_b32_e32 v65, 2, v0
	v_xor_b32_e32 v0, 16, v206
	v_cmp_lt_i32_e32 vcc, v0, v208
	s_nop 1
	v_cndmask_b32_e32 v0, v206, v0, vcc
	v_cmp_lt_i32_e32 vcc, v214, v208
	v_lshlrev_b32_e32 v66, 2, v0
	s_nop 0
	v_cndmask_b32_e32 v0, v206, v214, vcc
	v_lshlrev_b32_e32 v67, 2, v0
	global_load_dwordx4 v[76:79], v[30:31], off offset:16
	global_load_dwordx4 v[80:83], v[30:31], off
	global_load_dwordx4 v[84:87], v[30:31], off offset:2048
	global_load_dwordx4 v[88:91], v[30:31], off offset:2064
	s_branch .LBB0_109

; DI float bflo(unsigned w) { return __uint_as_float(w << 16); }
; DI float bfhi(unsigned w) { return __uint_as_float(w & 0xffff0000u); }
; DI void rw_phase(const float* x, bf16_t* hb, const bf16_t* y, const float* gpost, float* rh, float* fout, bool y_unscaled) {
;     ...
;     if (y) {
;       float yv[16]; float ss = 0.f;
; #pragma unroll
;       for (int c = 0; c < 2; ++c) {
;         const u32x4 w = gld<u32x4>(y + (size_t)row * 1024 + 512 * c + 8 * lane);
;         yv[8 * c + 0] = bflo(w.x); yv[8 * c + 1] = bfhi(w.x); yv[8 * c + 2] = bflo(w.y); yv[8 * c + 3] = bfhi(w.y);
;         yv[8 * c + 4] = bflo(w.z); yv[8 * c + 5] = bfhi(w.z); yv[8 * c + 6] = bflo(w.w); yv[8 * c + 7] = bfhi(w.w);
;       }
; #pragma unroll
;       for (int i = 0; i < 16; ++i) ss += yv[i] * yv[i];
;       ss = wave_sum(ss);
;       float epsn = EPS;
;       if (y_unscaled) { const float r = gld<float>(rh + row), r2 = r * r; epsn = EPS / (r2 * r2); }
;       const float ry = rsqrtf(ss * (1.0f / 1024.0f) + epsn);
; #pragma unroll
;       for (int c = 0; c < 2; ++c) {
;         const f32x4 g0 = gld<f32x4>(gpost + 512 * c + 8 * lane), g1 = gld<f32x4>(gpost + 512 * c + 8 * lane + 4);
; #pragma unroll
;         for (int i = 0; i < 4; ++i) { hv[8 * c + i] += yv[8 * c + i] * ry * g0[i]; hv[8 * c + 4 + i] += yv[8 * c + 4 + i] * ry * g1[i]; }
;       }
;     }
;     if (fout) {
;       float* op = fout + (size_t)row * 1024;
; #pragma unroll
;       for (int c = 0; c < 2; ++c) {
;         gst<f32x4>(op + 512 * c + 8 * lane, (f32x4){hv[8 * c], hv[8 * c + 1], hv[8 * c + 2], hv[8 * c + 3]});
;         gst<f32x4>(op + 512 * c + 8 * lane + 4, (f32x4){hv[8 * c + 4], hv[8 * c + 5], hv[8 * c + 6], hv[8 * c + 7]});
;       }
.LBB0_109:
	v_ashrrev_i32_e32 v25, 31, v24
	s_waitcnt lgkmcnt(0)
	v_lshlrev_b64 v[0:1], 11, v[24:25]
	v_lshl_add_u64 v[34:35], v[24:25], 2, s[74:75]
	v_lshl_add_u64 v[36:37], v[26:27], 0, v[0:1]
	global_load_dword v16, v[34:35], off
	global_load_dwordx4 v[8:11], v[36:37], off offset:1024
	v_lshl_add_u64 v[0:1], v[28:29], 0, v[0:1]
	global_load_dwordx4 v[12:15], v[0:1], off offset:1024
	global_load_dwordx4 v[54:57], v[0:1], off
	global_load_dwordx4 v[68:71], v[36:37], off
	s_nop 0
	s_waitcnt vmcnt(0)
	v_lshlrev_b32_e32 v22, 16, v12
	v_lshlrev_b32_e32 v52, 16, v54
	v_and_b32_e32 v53, 0xffff0000, v54
	v_lshlrev_b32_e32 v50, 16, v55
	v_and_b32_e32 v51, 0xffff0000, v55
	v_pk_mul_f32 v[54:55], v[52:53], v[52:53]
	v_lshlrev_b32_e32 v42, 16, v9
	v_and_b32_e32 v43, 0xffff0000, v9
	v_add_f32_e32 v9, v54, v55
	v_pk_mul_f32 v[54:55], v[50:51], v[50:51]
	v_lshlrev_b32_e32 v48, 16, v56
	v_and_b32_e32 v49, 0xffff0000, v56
	v_add_f32_e32 v9, v54, v9
	v_add_f32_e32 v9, v55, v9
	v_pk_mul_f32 v[54:55], v[48:49], v[48:49]
	v_lshlrev_b32_e32 v46, 16, v57
	v_and_b32_e32 v47, 0xffff0000, v57
	v_add_f32_e32 v9, v54, v9
	v_add_f32_e32 v9, v55, v9
	v_pk_mul_f32 v[54:55], v[46:47], v[46:47]
	v_and_b32_e32 v23, 0xffff0000, v12
	v_add_f32_e32 v9, v54, v9
	v_add_f32_e32 v9, v55, v9
	v_pk_mul_f32 v[54:55], v[22:23], v[22:23]
	v_lshlrev_b32_e32 v20, 16, v13
	v_and_b32_e32 v21, 0xffff0000, v13
	v_add_f32_e32 v9, v54, v9
	v_mul_f32_e32 v61, v16, v16
	v_lshlrev_b32_e32 v16, 16, v15
	v_and_b32_e32 v17, 0xffff0000, v15
	v_lshlrev_b32_e32 v18, 16, v14
	v_and_b32_e32 v19, 0xffff0000, v14
	v_pk_mul_f32 v[14:15], v[20:21], v[20:21]
	v_add_f32_e32 v9, v55, v9
	v_add_f32_e32 v9, v14, v9
	v_pk_mul_f32 v[12:13], v[18:19], v[18:19]
	v_add_f32_e32 v9, v15, v9
	v_add_f32_e32 v9, v12, v9
	v_lshlrev_b32_e32 v38, 16, v11
	v_and_b32_e32 v39, 0xffff0000, v11
	v_lshlrev_b32_e32 v40, 16, v10
	v_and_b32_e32 v41, 0xffff0000, v10
	v_pk_mul_f32 v[10:11], v[16:17], v[16:17]
	v_add_f32_e32 v9, v13, v9
	v_add_f32_e32 v9, v10, v9
	v_add_f32_e32 v9, v11, v9
	s_nop 1
	v_mov_b32_dpp v10, v9 quad_perm:[1,0,3,2] row_mask:0xf bank_mask:0xf
	v_lshlrev_b32_e32 v44, 16, v8
	v_and_b32_e32 v45, 0xffff0000, v8
	v_lshlrev_b32_e32 v58, 16, v69
	v_and_b32_e32 v59, 0xffff0000, v69
	s_waitcnt lgkmcnt(0)
	v_add_f32_e32 v8, v9, v10
	s_nop 1
	v_mov_b32_dpp v9, v8 quad_perm:[2,3,0,1] row_mask:0xf bank_mask:0xf
	v_mul_f32_e32 v10, v61, v61
	v_div_scale_f32 v11, s[44:45], v10, v10, s64
	v_rcp_f32_e32 v12, v11
	s_waitcnt lgkmcnt(0)
	v_add_f32_e32 v8, v8, v9
	s_nop 1
	v_mov_b32_dpp v9, v8 row_half_mirror row_mask:0xf bank_mask:0xf
	v_div_scale_f32 v13, vcc, s64, v10, s64
	v_fma_f32 v14, -v11, v12, 1.0
	v_fmac_f32_e32 v12, v14, v12
	s_waitcnt lgkmcnt(0)
	v_add_f32_e32 v8, v8, v9
	s_nop 1
	v_mov_b32_dpp v9, v8 row_mirror row_mask:0xf bank_mask:0xf
	v_mul_f32_e32 v14, v13, v12
	v_fma_f32 v15, -v11, v14, v13
	v_fmac_f32_e32 v14, v15, v12
	v_fma_f32 v11, -v11, v14, v13
	s_waitcnt lgkmcnt(0)
	v_add_f32_e32 v8, v8, v9
	v_mov_b32_e32 v9, v8
	v_mov_b32_e32 v120, v8
	s_nop 1
	v_permlane16_swap_b32_e32 v9, v120
	v_div_fmas_f32 v11, v11, v12, v14
	v_lshlrev_b32_e32 v60, 16, v68
	v_and_b32_e32 v61, 0xffff0000, v68
	v_div_fixup_f32 v68, v11, v10, s64
	s_waitcnt lgkmcnt(0)
	v_add_f32_e32 v8, v9, v120
	v_mov_b32_e32 v9, v8
	v_mov_b32_e32 v120, v8
	s_nop 1
	v_permlane32_swap_b32_e32 v9, v120
	v_lshlrev_b32_e32 v54, 16, v71
	v_and_b32_e32 v55, 0xffff0000, v71
	v_lshlrev_b32_e32 v56, 16, v70
	v_and_b32_e32 v57, 0xffff0000, v70
	s_waitcnt lgkmcnt(0)
	v_add_f32_e32 v69, v9, v120
	v_fmac_f32_e32 v68, 0x3a800000, v69
	v_mul_f32_e32 v69, 0x4b800000, v68
	v_cmp_gt_f32_e32 vcc, s33, v68
	s_and_b64 s[44:45], exec, s[38:39]
	s_nop 0
	v_cndmask_b32_e32 v68, v68, v69, vcc
	v_rsq_f32_e32 v68, v68
	s_nop 0
	v_mul_f32_e32 v69, 0x45800000, v68
	v_cndmask_b32_e32 v68, v68, v69, vcc
	v_pk_mul_f32 v[52:53], v[68:69], v[52:53] op_sel_hi:[0,1]
	v_pk_mul_f32 v[48:49], v[68:69], v[48:49] op_sel_hi:[0,1]
	v_pk_mul_f32 v[50:51], v[68:69], v[50:51] op_sel_hi:[0,1]
	v_pk_mul_f32 v[46:47], v[68:69], v[46:47] op_sel_hi:[0,1]
	v_pk_mul_f32 v[70:71], v[68:69], v[22:23] op_sel_hi:[0,1]
	v_pk_mul_f32 v[72:73], v[68:69], v[18:19] op_sel_hi:[0,1]
	v_pk_mul_f32 v[74:75], v[68:69], v[20:21] op_sel_hi:[0,1]
	v_pk_mul_f32 v[68:69], v[68:69], v[16:17] op_sel_hi:[0,1]
	v_pk_fma_f32 v[20:21], v[80:81], v[52:53], v[60:61]
	v_pk_fma_f32 v[16:17], v[76:77], v[48:49], v[56:57]
	v_pk_fma_f32 v[22:23], v[82:83], v[50:51], v[58:59]
	v_pk_fma_f32 v[18:19], v[78:79], v[46:47], v[54:55]
	s_mov_b64 vcc, s[44:45]
	s_waitcnt vmcnt(1)
	v_pk_fma_f32 v[4:5], v[84:85], v[70:71], v[44:45]
	s_waitcnt vmcnt(0)
	v_pk_fma_f32 v[0:1], v[88:89], v[72:73], v[40:41]
	v_pk_fma_f32 v[6:7], v[86:87], v[74:75], v[42:43]
	v_pk_fma_f32 v[2:3], v[90:91], v[68:69], v[38:39]
	s_cbranch_vccz .LBB0_111
	v_lshlrev_b64 v[8:9], 12, v[24:25]
	v_lshl_add_u64 v[8:9], v[32:33], 0, v[8:9]
	global_store_dwordx4 v[8:9], v[20:23], off
	global_store_dwordx4 v[8:9], v[16:19], off offset:16
	global_store_dwordx4 v[8:9], v[4:7], off offset:2048
	global_store_dwordx4 v[8:9], v[0:3], off offset:2064
	s_cbranch_execnz .LBB0_108
	s_branch .LBB0_112

; DI bf16_t tobf(float f) { return (bf16_t)(pk(f, 0.f) & 0xffffu); }
; DI int otid() { int t = threadIdx.x; asm volatile("" : "+v"(t)); return t; }
; template <int DK, bool GLA>
; DI void ppass_phase(const bf16_t* Qf, const bf16_t* Kf, const bf16_t* Qb, const bf16_t* Kb, int ld, const float* decay, bf16_t* P) {
;   const int tid_ = otid(), wid = tid_ >> 6, lane = tid_ & 63, fr = lane & 15, fq = lane >> 4;
;   const int rt = wid >> 1, ct0 = 2 * (wid & 1);
;   for (int item = blockIdx.x; item < 2048; item += gridDim.x) {
;     const int n = item & 127, h = (item >> 7) & 3, b = item >> 9;
;     const size_t tok0 = (size_t)b * L_ + n * 64;
;     f32x4 xf[2] = {}, xb[2] = {};
;     const bf16_t* qa = Qf + (tok0 + 16 * rt + fr) * ld + h * DK + 8 * fq;
;     const bf16_t* ka0 = Kf + (tok0 + 16 * ct0 + fr) * ld + h * DK + 8 * fq;
;     const bf16_t* ka1 = ka0 + (size_t)16 * ld;
;     ...
;     for (int c = 0; c < 2; ++c)
; #pragma unroll
;       for (int j = 0; j < 4; ++j) {
;         const int i = 16 * rt + 4 * fq + j, s = 16 * (ct0 + c) + fr;
;         float v;
;         if (GLA) v = (s <= i) ? xf[c][j] : xb[c][j];
;         else v = xf[c][j];
;         gst<bf16_t>(Po + i * 64 + s, tobf(v));
.LBB0_813:
	s_movk_i32 s70, 0x400
	s_mov_b64 s[76:77], 0
	s_and_b64 vcc, exec, s[42:43]
	s_mov_b64 s[52:53], 0
	s_cbranch_vccz .LBB0_894
	s_cmp_gt_i32 s91, 0
	s_mov_b64 s[0:1], -1
	s_cbranch_scc0 .LBB0_893
	v_readlane_b32 s64, v255, 39
	s_cmp_gt_i32 s91, 1
	s_mov_b32 s59, 0x8000
	s_movk_i32 s60, 0x3000
	s_movk_i32 s61, 0x6000
	s_movk_i32 s62, 0x2000
	v_readlane_b32 s65, v255, 40
	s_cbranch_scc0 .LBB0_820
	v_readlane_b32 s0, v254, 58
	v_readlane_b32 s1, v254, 59
	v_mov_b32_e32 v0, v159
	s_andn2_b64 vcc, exec, s[0:1]
	s_cbranch_vccnz .LBB0_819
	s_waitcnt lgkmcnt(0)
	v_and_b32_e32 v1, 15, v0
	v_bfe_u32 v3, v0, 4, 2
	v_ashrrev_i32_e32 v2, 3, v0
	v_lshrrev_b32_e32 v0, 1, v0
	v_and_b32_e32 v7, -16, v2
	v_and_or_b32 v6, v0, 32, v1
	s_add_u32 s0, s20, 0xa000400
	v_or_b32_e32 v4, v7, v1
	v_lshl_or_b32 v0, v3, 2, v7
	v_or_b32_e32 v1, 16, v6
	s_addc_u32 s1, s21, 0
	v_ashrrev_i32_e32 v5, 31, v7
	v_lshlrev_b32_e32 v2, 3, v3
	v_cmp_gt_i32_e32 vcc, v1, v0
	v_cmp_gt_i32_e64 s[42:43], v6, v0
	v_lshlrev_b32_e32 v8, 6, v0
	v_or_b32_e32 v3, 1, v0
	v_or_b32_e32 v7, 2, v0
	v_or_b32_e32 v0, 3, v0
	v_readlane_b32 s38, v255, 41
	s_add_u32 s22, s20, 0xe000400
	v_lshlrev_b32_e32 v10, 6, v3
	v_lshlrev_b32_e32 v12, 6, v7
	v_lshlrev_b32_e32 v14, 6, v0
	v_lshlrev_b32_e32 v148, 1, v6
	v_readlane_b32 s39, v255, 42
	s_addc_u32 s23, s21, 0
	v_ashrrev_i32_e32 v9, 31, v8
	v_cmp_gt_i32_e64 s[44:45], v6, v3
	v_ashrrev_i32_e32 v11, 31, v10
	v_cmp_gt_i32_e64 s[46:47], v6, v7
	v_ashrrev_i32_e32 v13, 31, v12
	v_cmp_gt_i32_e64 s[48:49], v6, v0
	v_ashrrev_i32_e32 v15, 31, v14
	v_cmp_gt_i32_e64 s[50:51], v1, v3
	v_cmp_gt_i32_e64 s[52:53], v1, v7
	v_cmp_gt_i32_e64 s[54:55], v1, v0
	v_lshl_add_u64 v[16:17], s[38:39], 0, v[148:149]
	v_lshrrev_b32_e32 v74, 7, v159
	v_and_b32_e32 v75, 15, v159
	v_lshl_or_b32 v74, v74, 4, v75
	v_bfe_u32 v75, v159, 6, 1
	v_bfe_u32 v76, v159, 4, 2
	v_lshlrev_b32_e32 v76, 2, v76
	v_lshl_or_b32 v75, v75, 5, v76
	v_lshlrev_b32_e32 v76, 7, v74
	v_lshl_or_b32 v76, v75, 1, v76
	v_mov_b32_e32 v77, 0
	v_lshl_add_u64 v[72:73], s[38:39], 0, v[76:77]
	v_cmp_gt_i32_e64 s[42:43], v75, v74
	v_add_u32_e32 v76, 1, v75
	v_cmp_gt_i32_e64 s[44:45], v76, v74
	v_add_u32_e32 v76, 2, v75
	v_cmp_gt_i32_e64 s[46:47], v76, v74
	v_add_u32_e32 v76, 3, v75
	v_cmp_gt_i32_e64 s[48:49], v76, v74
	v_add_u32_e32 v76, 16, v75
	v_cmp_gt_i32_e32 vcc, v76, v74
	v_add_u32_e32 v76, 17, v75
	v_cmp_gt_i32_e64 s[50:51], v76, v74
	v_add_u32_e32 v76, 18, v75
	v_cmp_gt_i32_e64 s[52:53], v76, v74
	v_add_u32_e32 v76, 19, v75
	v_cmp_gt_i32_e64 s[54:55], v76, v74
	v_lshlrev_b32_e32 v148, 1, v2
	s_mov_b32 s5, s2
; DI bf16_t tobf(float f) { return (bf16_t)(pk(f, 0.f) & 0xffffu); }
; template <int DK, bool GLA>
; DI void ppass_phase(const bf16_t* Qf, const bf16_t* Kf, const bf16_t* Qb, const bf16_t* Kb, int ld, const float* decay, bf16_t* P) {
;     ...
;   for (int item = blockIdx.x; item < 2048; item += gridDim.x) {
;     const int n = item & 127, h = (item >> 7) & 3, b = item >> 9;
;     const size_t tok0 = (size_t)b * L_ + n * 64;
;     f32x4 xf[2] = {}, xb[2] = {};
;     const bf16_t* qa = Qf + (tok0 + 16 * rt + fr) * ld + h * DK + 8 * fq;
;     const bf16_t* ka0 = Kf + (tok0 + 16 * ct0 + fr) * ld + h * DK + 8 * fq;
;     const bf16_t* ka1 = ka0 + (size_t)16 * ld;
; #pragma unroll
;     for (int kk = 0; kk < DK / 32; ++kk) {
;       const bf16x8 a = gld<bf16x8>(qa + 32 * kk), b0 = gld<bf16x8>(ka0 + 32 * kk), b1 = gld<bf16x8>(ka1 + 32 * kk);
;       xf[0] = __builtin_amdgcn_mfma_f32_16x16x32_bf16(a, b0, xf[0], 0, 0, 0);
;       xf[1] = __builtin_amdgcn_mfma_f32_16x16x32_bf16(a, b1, xf[1], 0, 0, 0);
;     }
;     if (GLA) {
;       const bf16_t* qb = Qb + (tok0 + 16 * rt + fr) * ld + h * DK + 8 * fq;
;       const bf16_t* kb0 = Kb + (tok0 + 16 * ct0 + fr) * ld + h * DK + 8 * fq;
;       const bf16_t* kb1 = kb0 + (size_t)16 * ld;
; #pragma unroll
;       for (int kk = 0; kk < DK / 32; ++kk) {
;         const bf16x8 a = gld<bf16x8>(qb + 32 * kk), b0 = gld<bf16x8>(kb0 + 32 * kk), b1 = gld<bf16x8>(kb1 + 32 * kk);
;         xb[0] = __builtin_amdgcn_mfma_f32_16x16x32_bf16(a, b0, xb[0], 0, 0, 0);
;         xb[1] = __builtin_amdgcn_mfma_f32_16x16x32_bf16(a, b1, xb[1], 0, 0, 0);
;       }
;     }
;     bf16_t* Po = P + (size_t)item * 4096;
;     Po = P + ((size_t)((b * 128 + n) * 4 + h)) * 4096;
; #pragma unroll
;     for (int c = 0; c < 2; ++c)
; #pragma unroll
;       for (int j = 0; j < 4; ++j) {
;         const int i = 16 * rt + 4 * fq + j, s = 16 * (ct0 + c) + fr;
;         float v;
;         if (GLA) v = (s <= i) ? xf[c][j] : xb[c][j];
;         else v = xf[c][j];
;         gst<bf16_t>(Po + i * 64 + s, tobf(v));
;       }
;   }
.LBB0_818:
	s_ashr_i32 s56, s5, 9
	s_and_b32 s39, s5, 0x7f
	s_ashr_i32 s57, s56, 31
	s_lshl_b32 s58, s39, 6
	s_lshl_b64 s[56:57], s[56:57], 13
	s_or_b32 s56, s56, s58
	v_mov_b32_e32 v1, s57
	v_or_b32_e32 v0, s56, v6
	s_bfe_u32 s38, s5, 0x20007
	v_lshlrev_b64 v[0:1], 11, v[0:1]
	s_lshl_b32 s24, s38, 8
	v_lshl_add_u64 v[20:21], s[0:1], 0, v[0:1]
	v_lshl_add_u64 v[20:21], v[20:21], 0, s[24:25]
	v_lshl_add_u64 v[2:3], v[4:5], 0, s[56:57]
	v_lshl_add_u64 v[0:1], s[22:23], 0, v[0:1]
	s_waitcnt vmcnt(0)
	v_lshl_add_u64 v[66:67], v[20:21], 0, v[148:149]
	v_lshlrev_b64 v[2:3], 11, v[2:3]
	v_lshl_add_u64 v[0:1], v[0:1], 0, s[24:25]
	v_add_co_u32_e64 v68, s[56:57], s59, v66
	v_lshl_add_u64 v[18:19], s[64:65], 0, v[2:3]
	v_lshl_add_u64 v[2:3], s[26:27], 0, v[2:3]
	v_lshl_add_u64 v[64:65], v[0:1], 0, v[148:149]
	v_addc_co_u32_e64 v69, s[56:57], 0, v67, s[56:57]
	v_lshl_add_u64 v[18:19], v[18:19], 0, s[24:25]
	v_lshl_add_u64 v[2:3], v[2:3], 0, s[24:25]
	v_add_co_u32_e64 v70, s[56:57], s59, v64
	v_lshl_add_u64 v[58:59], v[18:19], 0, v[148:149]
	v_lshl_add_u64 v[62:63], v[2:3], 0, v[148:149]
	v_addc_co_u32_e64 v71, s[56:57], 0, v65, s[56:57]
	global_load_dwordx4 v[0:3], v[66:67], off
	global_load_dwordx4 v[18:21], v[58:59], off
	global_load_dwordx4 v[22:25], v[58:59], off offset:64
	global_load_dwordx4 v[26:29], v[62:63], off
	global_load_dwordx4 v[30:33], v[62:63], off offset:64
	global_load_dwordx4 v[34:37], v[64:65], off
	global_load_dwordx4 v[38:41], v[64:65], off offset:64
	global_load_dwordx4 v[42:45], v[68:69], off
	global_load_dwordx4 v[46:49], v[68:69], off offset:64
	global_load_dwordx4 v[50:53], v[70:71], off
	global_load_dwordx4 v[54:57], v[70:71], off offset:64
	s_and_b32 s24, s5, 0xfffffe00
	s_lshl_b32 s39, s39, 2
	s_or_b32 s24, s39, s24
	s_or_b32 s38, s24, s38
	s_ashr_i32 s39, s38, 31
	s_lshl_b64 s[38:39], s[38:39], 13
	s_add_i32 s5, s5, s78
	s_cmpk_gt_i32 s5, 0x7ff
	s_waitcnt vmcnt(5)
	v_mfma_f32_16x16x32_bf16 v[34:37], v[34:37], v[26:29], 0
	s_waitcnt vmcnt(1)
	v_mfma_f32_16x16x32_bf16 v[26:29], v[50:53], v[26:29], 0
	global_load_dwordx4 v[50:53], v[66:67], off offset:64
	v_mfma_f32_16x16x32_bf16 v[42:45], v[42:45], v[18:21], 0
	v_mfma_f32_16x16x32_bf16 v[18:21], v[0:3], v[18:21], 0
	v_mfma_f32_16x16x32_bf16 v[42:45], v[46:49], v[22:25], v[42:45]
	global_load_dwordx4 v[46:49], v[66:67], off offset:128
	v_mfma_f32_16x16x32_bf16 v[34:37], v[38:41], v[30:33], v[34:37]
	global_load_dwordx4 v[38:41], v[58:59], off offset:128
	global_load_dwordx4 v[0:3], v[58:59], off offset:192
	s_nop 0
	global_load_dwordx4 v[58:61], v[62:63], off offset:128
	s_waitcnt vmcnt(5)
	v_mfma_f32_16x16x32_bf16 v[26:29], v[54:57], v[30:33], v[26:29]
	global_load_dwordx4 v[30:33], v[62:63], off offset:192
	global_load_dwordx4 v[54:57], v[64:65], off offset:128
	s_nop 0
	global_load_dwordx4 v[62:65], v[64:65], off offset:192
	s_waitcnt vmcnt(7)
	v_mfma_f32_16x16x32_bf16 v[18:21], v[50:53], v[22:25], v[18:21]
	global_load_dwordx4 v[22:25], v[68:69], off offset:128
	global_load_dwordx4 v[50:53], v[68:69], off offset:192
	s_waitcnt vmcnt(3)
	v_mfma_f32_16x16x32_bf16 v[34:37], v[54:57], v[58:61], v[34:37]
	global_load_dwordx4 v[54:57], v[70:71], off offset:192
	v_mfma_f32_16x16x32_bf16 v[18:21], v[46:49], v[38:41], v[18:21]
	s_waitcnt vmcnt(3)
	v_mfma_f32_16x16x32_bf16 v[34:37], v[62:65], v[30:33], v[34:37]
	s_waitcnt vmcnt(2)
	v_mfma_f32_16x16x32_bf16 v[22:25], v[22:25], v[38:41], v[42:45]
	s_nop 2
	global_load_dwordx4 v[42:45], v[70:71], off offset:128
	v_lshl_add_u64 v[38:39], v[72:73], 0, s[38:39]
	s_waitcnt vmcnt(2)
	v_mfma_f32_16x16x32_bf16 v[22:25], v[50:53], v[0:3], v[22:25]
	s_waitcnt vmcnt(0)
	v_mfma_f32_16x16x32_bf16 v[26:29], v[42:45], v[58:61], v[26:29]
	global_load_dwordx4 v[42:45], v[66:67], off offset:192
	v_mfma_f32_16x16x32_bf16 v[26:29], v[54:57], v[30:33], v[26:29]
	s_waitcnt vmcnt(0)
	v_mfma_f32_16x16x32_bf16 v[0:3], v[42:45], v[0:3], v[18:21]
	s_nop 2
	v_cndmask_b32_e32 v7, v22, v26, vcc
	v_cndmask_b32_e64 v18, v23, v27, s[50:51]
	v_cndmask_b32_e64 v19, v24, v28, s[52:53]
	s_nop 1
	v_cndmask_b32_e64 v0, v0, v34, s[42:43]
	v_cndmask_b32_e64 v1, v1, v35, s[44:45]
	v_cndmask_b32_e64 v2, v2, v36, s[46:47]
	v_cndmask_b32_e64 v3, v3, v37, s[48:49]
	v_cndmask_b32_e64 v20, v25, v29, s[54:55]
	v_cvt_pk_bf16_f32 v0, v0, v1
	v_cvt_pk_bf16_f32 v1, v2, v3
	v_cvt_pk_bf16_f32 v18, v7, v18
	v_cvt_pk_bf16_f32 v19, v19, v20
	global_store_dwordx2 v[38:39], v[0:1], off
	global_store_dwordx2 v[38:39], v[18:19], off offset:32
	s_cbranch_scc0 .LBB0_818
